# lever 7: x-conv part 2 address arithmetic hoisted (row step in the ds_write offset, one mode branch)
# baseline (speedup 1.0000x reference)
; DI unsigned pk2(float lo, float hi) { f32x2 v = {lo, hi}; bf2_t r = __builtin_convertvector(v, bf2_t); return __builtin_bit_cast(unsigned, r); }
; DI void ssd_scan_phase(bf16_t* P, const bf16_t* BT, const bf16_t* Cc, const bf16_t* CB, const float* dt, const float* acs,
;                        const float* cw, const float* cb, const float* Dp, char* lds, bool dry, int mode, float* Sbuf) {
;     ...
;           const float e127 = cAcs[127];
;           const float dlA = cDt[xl], dlB = cDt[xl + 1];
;           const float dsA = dlA * __expf(e127 - cAcs[xl]), dsB = dlB * __expf(e127 - cAcs[xl + 1]);
; #pragma unroll
;           for (int e = 0; e < 8; ++e) {
;             const int pr = xc * 8 + e;
;             const int off = pr * 256 + (((xl >> 3) ^ (pr & 15)) << 4) + (xl & 7) * 2;
;             if (mode == 0) *(unsigned*)(sXdt + off) = pk2(a[e] * dlA, bq[e] * dlB);
;             *(unsigned*)(sXds + off) = pk2(a[e] * dsA, bq[e] * dsB);
;           }
.LBB0_1065:
	s_lshl_b32 s81, s90, 7
	s_lshl_b32 s81, s81, 2
	s_add_i32 s81, s81, 0
	v_lshlrev_b32_e32 v36, 2, v40
	v_add_u32_e32 v37, s81, v36
	v_mov_b32_e32 v38, s88
	v_add_u32_e32 v37, 0x22c00, v37
	v_add_u32_e32 v39, s88, v36
	ds_read_b32 v44, v38 offset:508
	ds_read2_b32 v[36:37], v37 offset1:1
	ds_read2_b32 v[38:39], v39 offset1:1
	v_lshlrev_b32_e32 v42, 3, v41
	v_lshrrev_b32_e32 v43, 3, v40
	v_lshlrev_b32_e32 v40, 1, v40
	v_lshlrev_b32_e32 v41, 11, v41
	v_bitop3_b32 v45, v42, v43, 8 bitop3:0x6c
	v_and_b32_e32 v40, 14, v40
	v_or_b32_e32 v41, v41, v40
	v_add_u32_e32 v46, 0x18000, v41
	v_add_u32_e32 v47, 0x1a000, v41
	s_waitcnt lgkmcnt(0)
	v_sub_f32_e32 v38, v44, v38
	v_sub_f32_e32 v39, v44, v39
	v_mul_f32_e32 v38, 0x3fb8aa3b, v38
	v_mul_f32_e32 v39, 0x3fb8aa3b, v39
	v_exp_f32_e32 v38, v38
	v_exp_f32_e32 v39, v39
	s_nop 0
	v_pk_mul_f32 v[38:39], v[36:37], v[38:39]
	s_cmp_lg_u64 s[56:57], 0
	s_cbranch_scc1 .Lxc2_m1
	v_pk_mul_f32 v[42:43], v[34:35], v[36:37]
	v_pk_mul_f32 v[48:49], v[34:35], v[38:39]
	v_cvt_pk_bf16_f32 v42, v42, v43
	v_lshl_add_u32 v43, v45, 4, v46
	v_cvt_pk_bf16_f32 v48, v48, v49
	v_lshl_add_u32 v49, v45, 4, v47
	ds_write_b32 v43, v42
	ds_write_b32 v49, v48
	v_xor_b32_e32 v44, 1, v45
	v_pk_mul_f32 v[42:43], v[32:33], v[36:37]
	v_pk_mul_f32 v[48:49], v[32:33], v[38:39]
	v_cvt_pk_bf16_f32 v42, v42, v43
	v_lshl_add_u32 v43, v44, 4, v46
	v_cvt_pk_bf16_f32 v48, v48, v49
	v_lshl_add_u32 v49, v44, 4, v47
	ds_write_b32 v43, v42 offset:256
	ds_write_b32 v49, v48 offset:256
	v_xor_b32_e32 v44, 2, v45
	v_pk_mul_f32 v[42:43], v[28:29], v[36:37]
	v_pk_mul_f32 v[48:49], v[28:29], v[38:39]
	v_cvt_pk_bf16_f32 v42, v42, v43
	v_lshl_add_u32 v43, v44, 4, v46
	v_cvt_pk_bf16_f32 v48, v48, v49
	v_lshl_add_u32 v49, v44, 4, v47
	ds_write_b32 v43, v42 offset:512
	ds_write_b32 v49, v48 offset:512
	v_xor_b32_e32 v44, 3, v45
	v_pk_mul_f32 v[42:43], v[26:27], v[36:37]
	v_pk_mul_f32 v[48:49], v[26:27], v[38:39]
	v_cvt_pk_bf16_f32 v42, v42, v43
	v_lshl_add_u32 v43, v44, 4, v46
	v_cvt_pk_bf16_f32 v48, v48, v49
	v_lshl_add_u32 v49, v44, 4, v47
	ds_write_b32 v43, v42 offset:768
	ds_write_b32 v49, v48 offset:768
	v_xor_b32_e32 v44, 4, v45
	v_pk_mul_f32 v[42:43], v[24:25], v[36:37]
	v_pk_mul_f32 v[48:49], v[24:25], v[38:39]
	v_cvt_pk_bf16_f32 v42, v42, v43
	v_lshl_add_u32 v43, v44, 4, v46
	v_cvt_pk_bf16_f32 v48, v48, v49
	v_lshl_add_u32 v49, v44, 4, v47
	ds_write_b32 v43, v42 offset:1024
	ds_write_b32 v49, v48 offset:1024
	v_xor_b32_e32 v44, 5, v45
	v_pk_mul_f32 v[42:43], v[30:31], v[36:37]
	v_pk_mul_f32 v[48:49], v[30:31], v[38:39]
	v_cvt_pk_bf16_f32 v42, v42, v43
	v_lshl_add_u32 v43, v44, 4, v46
	v_cvt_pk_bf16_f32 v48, v48, v49
	v_lshl_add_u32 v49, v44, 4, v47
	ds_write_b32 v43, v42 offset:1280
	ds_write_b32 v49, v48 offset:1280
	v_xor_b32_e32 v44, 6, v45
	v_pk_mul_f32 v[42:43], v[22:23], v[36:37]
	v_pk_mul_f32 v[48:49], v[22:23], v[38:39]
	v_cvt_pk_bf16_f32 v42, v42, v43
	v_lshl_add_u32 v43, v44, 4, v46
	v_cvt_pk_bf16_f32 v48, v48, v49
	v_lshl_add_u32 v49, v44, 4, v47
	ds_write_b32 v43, v42 offset:1536
	ds_write_b32 v49, v48 offset:1536
	v_xor_b32_e32 v44, 7, v45
	v_pk_mul_f32 v[42:43], v[20:21], v[36:37]
	v_pk_mul_f32 v[48:49], v[20:21], v[38:39]
	v_cvt_pk_bf16_f32 v42, v42, v43
	v_lshl_add_u32 v43, v44, 4, v46
	v_cvt_pk_bf16_f32 v48, v48, v49
	v_lshl_add_u32 v49, v44, 4, v47
	ds_write_b32 v43, v42 offset:1792
	ds_write_b32 v49, v48 offset:1792
	s_branch .LBB0_1082
.Lxc2_m1:
	v_pk_mul_f32 v[48:49], v[34:35], v[38:39]
	v_cvt_pk_bf16_f32 v48, v48, v49
	v_lshl_add_u32 v49, v45, 4, v47
	ds_write_b32 v49, v48
	v_xor_b32_e32 v44, 1, v45
	v_pk_mul_f32 v[48:49], v[32:33], v[38:39]
	v_cvt_pk_bf16_f32 v48, v48, v49
	v_lshl_add_u32 v49, v44, 4, v47
	ds_write_b32 v49, v48 offset:256
	v_xor_b32_e32 v44, 2, v45
	v_pk_mul_f32 v[48:49], v[28:29], v[38:39]
	v_cvt_pk_bf16_f32 v48, v48, v49
	v_lshl_add_u32 v49, v44, 4, v47
	ds_write_b32 v49, v48 offset:512
	v_xor_b32_e32 v44, 3, v45
	v_pk_mul_f32 v[48:49], v[26:27], v[38:39]
	v_cvt_pk_bf16_f32 v48, v48, v49
	v_lshl_add_u32 v49, v44, 4, v47
	ds_write_b32 v49, v48 offset:768
	v_xor_b32_e32 v44, 4, v45
	v_pk_mul_f32 v[48:49], v[24:25], v[38:39]
	v_cvt_pk_bf16_f32 v48, v48, v49
	v_lshl_add_u32 v49, v44, 4, v47
	ds_write_b32 v49, v48 offset:1024
	v_xor_b32_e32 v44, 5, v45
	v_pk_mul_f32 v[48:49], v[30:31], v[38:39]
	v_cvt_pk_bf16_f32 v48, v48, v49
	v_lshl_add_u32 v49, v44, 4, v47
	ds_write_b32 v49, v48 offset:1280
	v_xor_b32_e32 v44, 6, v45
	v_pk_mul_f32 v[48:49], v[22:23], v[38:39]
	v_cvt_pk_bf16_f32 v48, v48, v49
	v_lshl_add_u32 v49, v44, 4, v47
	ds_write_b32 v49, v48 offset:1536
	v_xor_b32_e32 v44, 7, v45
	v_pk_mul_f32 v[48:49], v[20:21], v[38:39]
	v_cvt_pk_bf16_f32 v48, v48, v49
	v_lshl_add_u32 v49, v44, 4, v47
	ds_write_b32 v49, v48 offset:1792
